# S21 minus ten redundant self-max (canonicalize) VALU ops per iteration in the running-max code
# baseline (speedup 1.0000x reference)
; __device__ __forceinline__ void partialSM(f32x16& p0, f32x16& p1, float& m_reg, float& mn, float& alpha) {
;   constexpr float C = SCALE * 1.4426950408889634f;
;   float pmax = p0[0]; for (int r = 1; r < 16; ++r) pmax = fmaxf(pmax, p0[r]); for (int r = 0; r < 16; ++r) pmax = fmaxf(pmax, p1[r]);
;   { auto rr = __builtin_amdgcn_permlane32_swap(__float_as_uint(pmax), __float_as_uint(pmax), false, false);
;     pmax = fmaxf(__uint_as_float(rr[0]), __uint_as_float(rr[1])); }
;   if (__builtin_expect(__all(pmax - m_reg <= THR / SCALE), 1)) { mn = m_reg; alpha = 1.f; }
;   else { mn = fmaxf(m_reg, pmax); alpha = __builtin_amdgcn_exp2f((m_reg - mn) * C); m_reg = mn; }
;   float mnC = -mn * C;
;   for (int r = 0; r < 16; ++r) p0[r] = fmaf(p0[r], C, mnC); for (int r = 0; r < 16; ++r) p1[r] = fmaf(p1[r], C, mnC);
;   for (int r = 0; r < 16; ++r) p0[r] = __builtin_amdgcn_exp2f(p0[r]);
; }
; __device__ __forceinline__ void finishSM(f32x16& p0, f32x16& p1, float alpha, float& l_reg, bf16x8& pa0, bf16x8& pa1, bf16x8& pa2, bf16x8& pa3) {
;   for (int r = 0; r < 16; ++r) p1[r] = __builtin_amdgcn_exp2f(p1[r]);
;   float ps = 0; for (int r = 0; r < 16; ++r) ps += p0[r]; for (int r = 0; r < 16; ++r) ps += p1[r];
;   { auto rr = __builtin_amdgcn_permlane32_swap(__float_as_uint(ps), __float_as_uint(ps), false, false);
;     ps = __uint_as_float(rr[0]) + __uint_as_float(rr[1]); }
;   l_reg = l_reg * alpha + ps;
;     ...
;   PK4(p0, 0, pa0); PK4(p0, 8, pa1); PK4(p1, 0, pa2); PK4(p1, 8, pa3);
;     ...
; }
; __device__ __forceinline__ void kload(bf16x8 (&kf)[8], const char* Ks, int r32, int hi, int sb) {
; #pragma unroll
;   for (int d0 = 0; d0 < 4; ++d0) { const int cb = sb + (d0 * 16 + hi * 8) * 2;
;     kf[2 * d0] = *reinterpret_cast<const bf16x8*>(Ks + KSWZ(r32, cb)); kf[2 * d0 + 1] = *reinterpret_cast<const bf16x8*>(Ks + KSWZ(32 + r32, cb)); }
; }
; __device__ __forceinline__ void kmma(f32x16& p0, f32x16& p1, const bf16x8 (&kf)[8], const bf16x8* qr) {
;   asm volatile("s_waitcnt lgkmcnt(0)" ::: "memory"); SBAR();
;   p0 = f32x16{}; p1 = f32x16{};
; #pragma unroll
;   for (int d0 = 0; d0 < 4; ++d0) { p0 = __builtin_amdgcn_mfma_f32_32x32x16_bf16(kf[2 * d0], qr[d0], p0, 0, 0, 0); p1 = __builtin_amdgcn_mfma_f32_32x32x16_bf16(kf[2 * d0 + 1], qr[d0], p1, 0, 0, 0); }
; }
; __device__ __forceinline__ void qkt(f32x16& p0, f32x16& p1, const char* Ks, const bf16x8* qr, int r32, int hi, int sb) {
.LBB0_770:
	ds_read_b128 v[82:85], v245
	ds_read_b128 v[86:89], v245 offset:8192
	ds_read_b128 v[130:133], v246
	ds_read_b128 v[134:137], v246 offset:8192
	ds_read_b128 v[206:209], v247
	ds_read_b128 v[210:213], v247 offset:8192
	ds_read_b128 v[214:217], v255
	ds_read_b128 v[218:221], v255 offset:8192
	v_exp_f32_e32 v148, v66
	v_add_f32_e32 v66, 0, v175
	v_add_f32_e32 v66, v177, v66
	v_add_f32_e32 v66, v192, v66
	v_add_f32_e32 v66, v195, v66
	v_add_f32_e32 v66, v196, v66
	v_add_f32_e32 v66, v199, v66
	v_add_f32_e32 v66, v200, v66
	v_add_f32_e32 v66, v203, v66
	v_add_f32_e32 v66, v176, v66
	v_add_f32_e32 v66, v193, v66
	v_add_f32_e32 v66, v194, v66
	v_add_f32_e32 v66, v197, v66
	v_add_f32_e32 v66, v198, v66
	v_exp_f32_e32 v149, v67
	v_add_f32_e32 v66, v201, v66
	s_waitcnt lgkmcnt(7)
	v_mfma_f32_32x32x16_bf16 v[98:113], v[82:85], v[126:129], 0
	v_exp_f32_e32 v150, v68
	s_and_b32 s13, s36, 0xc000
	v_add_f32_e32 v66, v202, v66
	v_add_u32_e32 v244, s13, v164
	v_exp_f32_e32 v151, v69
	ds_read_b64_tr_b16 v[228:229], v244 offset:0
	v_add_f32_e32 v66, v204, v66
	ds_read_b64_tr_b16 v[230:231], v244 offset:0x800
	ds_read_b64_tr_b16 v[232:233], v244 offset:0x1000
	ds_read_b64_tr_b16 v[234:235], v244 offset:0x1800
	s_waitcnt lgkmcnt(10)
	v_mfma_f32_32x32x16_bf16 v[82:97], v[86:89], v[126:129], 0
	v_exp_f32_e32 v186, v70
	ds_read_b64_tr_b16 v[236:237], v244 offset:0x2000
	v_add_f32_e32 v66, v148, v66
	ds_read_b64_tr_b16 v[238:239], v244 offset:0x2800
	v_exp_f32_e32 v187, v71
	ds_read_b64_tr_b16 v[240:241], v244 offset:0x3000
	v_add_f32_e32 v66, v149, v66
	ds_read_b64_tr_b16 v[242:243], v244 offset:0x3800
	v_exp_f32_e32 v188, v72
	s_add_i32 s37, s12, 2
	s_cmpk_lt_u32 s12, 0x7e
	s_cselect_b64 s[0:1], -1, 0
	s_waitcnt lgkmcnt(13)
	v_mfma_f32_32x32x16_bf16 v[98:113], v[130:133], v[122:125], v[98:113]
	v_add_f32_e32 v66, v150, v66
	s_and_b64 s[10:11], s[0:1], exec
	v_exp_f32_e32 v189, v73
	s_cselect_b32 s10, 0, 0xffffff80
	v_add_f32_e32 v66, v151, v66
	s_add_i32 s58, s37, s10
	v_exp_f32_e32 v205, v74
	s_and_b64 s[0:1], s[0:1], exec
	s_cselect_b32 s1, s9, s30
	s_cselect_b32 s0, s8, s26
	s_lshl_b64 s[10:11], s[58:59], 17
	s_waitcnt lgkmcnt(12)
	v_mfma_f32_32x32x16_bf16 v[82:97], v[134:137], v[122:125], v[82:97]
	v_add_f32_e32 v66, v186, v66
	s_lshl_b64 s[0:1], s[0:1], 11
	v_exp_f32_e32 v222, v75
	s_add_u32 s10, s10, s0
	v_add_f32_e32 v66, v187, v66
	s_addc_u32 s11, s11, s1
	v_exp_f32_e32 v223, v76
	s_add_u32 s0, s20, s10
	v_add_f32_e32 v66, v188, v66
	s_addc_u32 s1, s21, s11
	s_add_u32 s10, s22, s10
	s_addc_u32 s11, s23, s11
	s_waitcnt lgkmcnt(11)
	v_mfma_f32_32x32x16_bf16 v[98:113], v[206:209], v[118:121], v[98:113]
	v_exp_f32_e32 v224, v77
	s_and_b32 s13, s37, 0xff
	v_add_f32_e32 v66, v189, v66
	s_mulk_i32 s13, 0xab
	v_exp_f32_e32 v225, v78
	s_lshr_b32 s13, s13, 9
	v_add_f32_e32 v66, v205, v66
	s_mul_i32 s13, s13, 3
	s_sub_i32 s13, s37, s13
	s_and_b32 s13, s13, 0xff
	s_waitcnt lgkmcnt(10)
	v_mfma_f32_32x32x16_bf16 v[82:97], v[210:213], v[118:121], v[82:97]
	v_exp_f32_e32 v226, v79
	s_lshl_b32 s13, s13, 14
	s_mov_b32 s100, s13
	v_add_f32_e32 v66, v222, v66
	s_add_i32 s42, s36, 0xffffc000
	v_exp_f32_e32 v227, v80
	s_and_b32 s42, s42, 0xc000
	v_add_f32_e32 v66, v223, v66
	s_add_i32 s13, s13, s27
	v_exp_f32_e32 v81, v81
	s_add_i32 s42, s42, s31
	s_mov_b32 m0, s13
	s_waitcnt lgkmcnt(9)
	v_mfma_f32_32x32x16_bf16 v[98:113], v[214:217], v[114:117], v[98:113]
	v_add_f32_e32 v66, v224, v66
	v_add_f32_e32 v66, v225, v66
	global_load_lds_dwordx4 v146, s[0:1]
	v_add_f32_e32 v66, v226, v66
	v_add_f32_e32 v66, v227, v66
	s_mov_b32 m0, s42
	s_nop 0
	global_load_lds_dwordx4 v142, s[10:11]
	s_waitcnt lgkmcnt(8)
	v_mfma_f32_32x32x16_bf16 v[82:97], v[218:221], v[114:117], v[82:97]
	v_add_f32_e32 v130, v81, v66
	s_add_i32 m0, s13, 0x2000
	v_mov_b32_e32 v131, v130
	v_cvt_pk_bf16_f32 v66, v175, v177
	global_load_lds_dwordx4 v144, s[0:1]
	v_cvt_pk_bf16_f32 v67, v192, v195
	v_cvt_pk_bf16_f32 v68, v196, v199
	s_add_i32 m0, s42, 0x2000
	s_nop 0
	global_load_lds_dwordx4 v154, s[10:11]
	v_permlane32_swap_b32_e32 v130, v131
	v_cvt_pk_bf16_f32 v69, v200, v203
	v_permlane32_swap_b32_e32 v66, v68
	v_cvt_pk_bf16_f32 v70, v176, v193
	v_cvt_pk_bf16_f32 v71, v194, v197
	v_cvt_pk_bf16_f32 v72, v198, v201
	v_cvt_pk_bf16_f32 v73, v202, v204
	v_cvt_pk_bf16_f32 v74, v148, v149
	v_cvt_pk_bf16_f32 v75, v150, v151
	v_cvt_pk_bf16_f32 v76, v186, v187
	v_cvt_pk_bf16_f32 v77, v188, v189
	v_cvt_pk_bf16_f32 v78, v205, v222
	v_cvt_pk_bf16_f32 v79, v223, v224
	v_cvt_pk_bf16_f32 v80, v225, v226
	v_cvt_pk_bf16_f32 v81, v227, v81
	v_permlane32_swap_b32_e32 v67, v69
	v_permlane32_swap_b32_e32 v70, v72
	v_permlane32_swap_b32_e32 v71, v73
	v_permlane32_swap_b32_e32 v74, v76
	v_permlane32_swap_b32_e32 v75, v77
	v_permlane32_swap_b32_e32 v78, v80
	v_permlane32_swap_b32_e32 v79, v81
	ds_read_b64_tr_b16 v[204:205], v244 offset:0x200
	ds_read_b64_tr_b16 v[206:207], v244 offset:0xa00
	ds_read_b64_tr_b16 v[208:209], v244 offset:0x1200
	ds_read_b64_tr_b16 v[210:211], v244 offset:0x1a00
	ds_read_b64_tr_b16 v[212:213], v244 offset:0x2200
	ds_read_b64_tr_b16 v[214:215], v244 offset:0x2a00
	ds_read_b64_tr_b16 v[216:217], v244 offset:0x3200
	ds_read_b64_tr_b16 v[218:219], v244 offset:0x3a00
	s_waitcnt lgkmcnt(14)
	v_mfma_f32_32x32x16_bf16 v[18:33], v[66:69], v[228:231], v[18:33]
	v_max_f32_e32 v245, v98, v99
	v_max3_f32 v245, v245, v100, v101
	v_max3_f32 v245, v245, v102, v103
	v_max3_f32 v245, v245, v104, v105
	v_max3_f32 v245, v245, v106, v107
	v_max3_f32 v245, v245, v108, v109
	s_waitcnt lgkmcnt(12)
; __device__ __forceinline__ void partialSM(f32x16& p0, f32x16& p1, float& m_reg, float& mn, float& alpha) {
;   constexpr float C = SCALE * 1.4426950408889634f;
;   float pmax = p0[0]; for (int r = 1; r < 16; ++r) pmax = fmaxf(pmax, p0[r]); for (int r = 0; r < 16; ++r) pmax = fmaxf(pmax, p1[r]);
;   { auto rr = __builtin_amdgcn_permlane32_swap(__float_as_uint(pmax), __float_as_uint(pmax), false, false);
;     pmax = fmaxf(__uint_as_float(rr[0]), __uint_as_float(rr[1])); }
;   if (__builtin_expect(__all(pmax - m_reg <= THR / SCALE), 1)) { mn = m_reg; alpha = 1.f; }
;   else { mn = fmaxf(m_reg, pmax); alpha = __builtin_amdgcn_exp2f((m_reg - mn) * C); m_reg = mn; }
;   float mnC = -mn * C;
;   for (int r = 0; r < 16; ++r) p0[r] = fmaf(p0[r], C, mnC); for (int r = 0; r < 16; ++r) p1[r] = fmaf(p1[r], C, mnC);
;   for (int r = 0; r < 16; ++r) p0[r] = __builtin_amdgcn_exp2f(p0[r]);
; }
; __device__ __forceinline__ void pv_mma(f32x16& od, const VFrag& f, bf16x8 pa0, bf16x8 pa1, bf16x8 pa2, bf16x8 pa3) {
;     ...
;   od = __builtin_amdgcn_mfma_f32_32x32x16_bf16(pa0, PK(f.l0, f.h0), od, 0, 0, 0);
;   od = __builtin_amdgcn_mfma_f32_32x32x16_bf16(pa1, PK(f.l1, f.h1), od, 0, 0, 0);
;   od = __builtin_amdgcn_mfma_f32_32x32x16_bf16(pa2, PK(f.l2, f.h2), od, 0, 0, 0);
;   od = __builtin_amdgcn_mfma_f32_32x32x16_bf16(pa3, PK(f.l3, f.h3), od, 0, 0, 0);
;     ...
; }
; __device__ __forceinline__ void pv_d0(f32x16* o, int vb, bf16x8 pa0, bf16x8 pa1, bf16x8 pa2, bf16x8 pa3) {
;   VFrag fa, fb;
;   v_frag_read<0>(fa, vb);
;   asm volatile("s_waitcnt lgkmcnt(0)" ::: "memory"); SBAR();
;   v_frag_read<1>(fb, vb); SBAR();
;   pv_mma(o[0], fa, pa0, pa1, pa2, pa3); SBAR();
;   asm volatile("s_waitcnt lgkmcnt(0)" ::: "memory"); SBAR();
;   v_frag_read<2>(fa, vb); SBAR();
;   pv_mma(o[1], fb, pa0, pa1, pa2, pa3); SBAR();
;   asm volatile("s_waitcnt lgkmcnt(0)" ::: "memory"); SBAR();
;   v_frag_read<3>(fb, vb); SBAR();
;   pv_mma(o[2], fa, pa0, pa1, pa2, pa3); SBAR();
;   asm volatile("s_waitcnt lgkmcnt(0)" ::: "memory"); SBAR();
;   pv_mma(o[3], fb, pa0, pa1, pa2, pa3);
; }
; __device__ __forceinline__ void attn_unit(const bf16* __restrict__ Qb, const bf16* __restrict__ Kh, const bf16* __restrict__ Vh, int klat0, int nlt, int kctx0, int NT,
;                                           float lam, float post, const float* __restrict__ subw, bf16* __restrict__ Ob, char* lds) {
	v_mfma_f32_32x32x16_bf16 v[18:33], v[70:73], v[232:235], v[18:33]
	v_max3_f32 v245, v245, v110, v111
	v_max3_f32 v245, v245, v112, v113
	v_max3_f32 v245, v245, v82, v83
	v_max3_f32 v245, v245, v84, v85
	v_max3_f32 v245, v245, v86, v87
	v_max3_f32 v245, v245, v88, v89
	v_max3_f32 v245, v245, v90, v91
	v_max3_f32 v245, v245, v92, v93
	s_waitcnt lgkmcnt(10)
	v_mfma_f32_32x32x16_bf16 v[18:33], v[74:77], v[236:239], v[18:33]
	v_max3_f32 v245, v245, v94, v95
	v_max3_f32 v245, v245, v96, v97
	v_mov_b32_e32 v246, v245
	s_nop 1
	v_permlane32_swap_b32_e32 v245, v246
	v_max_f32_e32 v245, v245, v246
	v_sub_f32_e32 v246, v245, v174
	s_waitcnt lgkmcnt(8)
	v_mfma_f32_32x32x16_bf16 v[18:33], v[78:81], v[240:243], v[18:33]
	v_cmp_ge_f32_e32 vcc, s63, v246
	v_max_f32_e32 v245, v174, v245
	v_sub_f32_e32 v246, v174, v245
	v_mul_f32_e32 v246, 0x3e38aa3b, v246
	v_exp_f32_e32 v246, v246
	s_cmp_eq_u64 vcc, exec
	s_cselect_b64 s[0:1], -1, 0
	v_cndmask_b32_e64 v132, v246, 1.0, s[0:1]
	ds_read_b64_tr_b16 v[228:229], v244 offset:0x400
	ds_read_b64_tr_b16 v[230:231], v244 offset:0xc00
	ds_read_b64_tr_b16 v[232:233], v244 offset:0x1400
	ds_read_b64_tr_b16 v[234:235], v244 offset:0x1c00
	ds_read_b64_tr_b16 v[236:237], v244 offset:0x2400
	ds_read_b64_tr_b16 v[238:239], v244 offset:0x2c00
	ds_read_b64_tr_b16 v[240:241], v244 offset:0x3400
	ds_read_b64_tr_b16 v[242:243], v244 offset:0x3c00
	v_cndmask_b32_e64 v133, v245, v174, s[0:1]
	v_mul_f32_e32 v148, 0xbe38aa3b, v133
	s_waitcnt lgkmcnt(14)
	v_mfma_f32_32x32x16_bf16 v[50:65], v[66:69], v[204:207], v[50:65]
	v_fmamk_f32 v98, v98, 0x3e38aa3b, v148
	v_fmamk_f32 v99, v99, 0x3e38aa3b, v148
	v_fmamk_f32 v100, v100, 0x3e38aa3b, v148
	v_fmamk_f32 v101, v101, 0x3e38aa3b, v148
	s_waitcnt lgkmcnt(12)
	v_mfma_f32_32x32x16_bf16 v[50:65], v[70:73], v[208:211], v[50:65]
	v_fmamk_f32 v102, v102, 0x3e38aa3b, v148
	v_fmamk_f32 v103, v103, 0x3e38aa3b, v148
	v_fmamk_f32 v104, v104, 0x3e38aa3b, v148
	v_fmamk_f32 v105, v105, 0x3e38aa3b, v148
	s_waitcnt lgkmcnt(10)
	v_mfma_f32_32x32x16_bf16 v[50:65], v[74:77], v[212:215], v[50:65]
	v_fmamk_f32 v106, v106, 0x3e38aa3b, v148
	v_fmamk_f32 v107, v107, 0x3e38aa3b, v148
	v_fmamk_f32 v108, v108, 0x3e38aa3b, v148
	v_fmamk_f32 v109, v109, 0x3e38aa3b, v148
	s_waitcnt lgkmcnt(8)
	v_mfma_f32_32x32x16_bf16 v[50:65], v[78:81], v[216:219], v[50:65]
	v_fmamk_f32 v110, v110, 0x3e38aa3b, v148
	v_fmamk_f32 v111, v111, 0x3e38aa3b, v148
	v_fmamk_f32 v112, v112, 0x3e38aa3b, v148
	v_fmamk_f32 v113, v113, 0x3e38aa3b, v148
	ds_read_b64_tr_b16 v[204:205], v244 offset:0x600
	ds_read_b64_tr_b16 v[206:207], v244 offset:0xe00
	ds_read_b64_tr_b16 v[208:209], v244 offset:0x1600
	ds_read_b64_tr_b16 v[210:211], v244 offset:0x1e00
	ds_read_b64_tr_b16 v[212:213], v244 offset:0x2600
	ds_read_b64_tr_b16 v[214:215], v244 offset:0x2e00
	ds_read_b64_tr_b16 v[216:217], v244 offset:0x3600
	ds_read_b64_tr_b16 v[218:219], v244 offset:0x3e00
	s_waitcnt lgkmcnt(14)
	v_mfma_f32_32x32x16_bf16 v[34:49], v[66:69], v[228:231], v[34:49]
	v_fmamk_f32 v82, v82, 0x3e38aa3b, v148
	v_fmamk_f32 v83, v83, 0x3e38aa3b, v148
	v_fmamk_f32 v84, v84, 0x3e38aa3b, v148
	v_fmamk_f32 v85, v85, 0x3e38aa3b, v148
	s_waitcnt lgkmcnt(12)
	v_mfma_f32_32x32x16_bf16 v[34:49], v[70:73], v[232:235], v[34:49]
	v_fmamk_f32 v86, v86, 0x3e38aa3b, v148
	v_fmamk_f32 v87, v87, 0x3e38aa3b, v148
	s_add_i32 s13, s36, 0xffff4000
	v_fmamk_f32 v149, v88, 0x3e38aa3b, v148
	s_waitcnt lgkmcnt(10)
	v_mfma_f32_32x32x16_bf16 v[34:49], v[74:77], v[236:239], v[34:49]
	v_fmamk_f32 v150, v89, 0x3e38aa3b, v148
	v_fmamk_f32 v151, v90, 0x3e38aa3b, v148
	v_fmamk_f32 v186, v91, 0x3e38aa3b, v148
	v_fmamk_f32 v187, v92, 0x3e38aa3b, v148
	s_waitcnt lgkmcnt(8)
	v_mfma_f32_32x32x16_bf16 v[34:49], v[78:81], v[240:243], v[34:49]
	v_fmamk_f32 v188, v93, 0x3e38aa3b, v148
	v_fmamk_f32 v189, v94, 0x3e38aa3b, v148
	v_exp_f32_e32 v192, v98
	v_exp_f32_e32 v193, v99
	v_exp_f32_e32 v194, v100
	v_exp_f32_e32 v195, v101
	s_waitcnt lgkmcnt(6)
	v_mfma_f32_32x32x16_bf16 v[2:17], v[66:69], v[204:207], v[2:17]
	v_exp_f32_e32 v196, v102
	v_exp_f32_e32 v197, v103
	v_exp_f32_e32 v198, v104
	v_exp_f32_e32 v199, v105
	s_waitcnt lgkmcnt(4)
	v_mfma_f32_32x32x16_bf16 v[2:17], v[70:73], v[208:211], v[2:17]
	v_exp_f32_e32 v200, v106
	v_exp_f32_e32 v201, v107
	v_exp_f32_e32 v202, v108
	v_exp_f32_e32 v203, v109
	v_exp_f32_e32 v204, v110
	v_exp_f32_e32 v205, v111
	s_waitcnt lgkmcnt(2)
	v_mfma_f32_32x32x16_bf16 v[2:17], v[74:77], v[212:215], v[2:17]
	v_exp_f32_e32 v206, v112
	v_exp_f32_e32 v207, v113
	v_fmamk_f32 v208, v95, 0x3e38aa3b, v148
	v_fmamk_f32 v209, v96, 0x3e38aa3b, v148
	v_fmac_f32_e32 v148, 0x3e38aa3b, v97
	s_waitcnt lgkmcnt(0)
	v_mfma_f32_32x32x16_bf16 v[2:17], v[78:81], v[216:219], v[2:17]
	v_add_u32_e32 v245, s101, v169
	v_add_u32_e32 v246, s101, v170
	v_add_u32_e32 v247, s101, v171
	v_add_u32_e32 v255, s101, v172
	v_cmp_gt_f32_e32 vcc, 1.0, v132
	s_cbranch_vccz .LBB0_774
	s_and_saveexec_b64 s[10:11], s[40:41]
	ds_write_b32 v162, v132 offset:128
	s_or_b64 exec, exec, s[10:11]
	s_waitcnt lgkmcnt(0)
	v_add_u32_e32 v67, s18, v140
	ds_read_b128 v[68:71], v67 offset:224
	ds_read_b128 v[72:75], v67 offset:192
	ds_read_b128 v[76:79], v67 offset:160
	ds_read_b128 v[134:137], v67 offset:128
	s_waitcnt lgkmcnt(0)
	v_pk_mul_f32 v[30:31], v[30:31], v[68:69]
	v_pk_mul_f32 v[26:27], v[26:27], v[72:73]
	v_pk_mul_f32 v[22:23], v[22:23], v[76:77]
	v_pk_mul_f32 v[32:33], v[32:33], v[70:71]
	v_pk_mul_f32 v[28:29], v[28:29], v[74:75]
	v_pk_mul_f32 v[24:25], v[24:25], v[78:79]
	v_pk_mul_f32 v[20:21], v[20:21], v[136:137]
	v_pk_mul_f32 v[18:19], v[18:19], v[134:135]
	v_pk_mul_f32 v[62:63], v[62:63], v[68:69]
	v_pk_mul_f32 v[58:59], v[58:59], v[72:73]
	v_pk_mul_f32 v[54:55], v[54:55], v[76:77]
	v_pk_mul_f32 v[64:65], v[64:65], v[70:71]
	v_pk_mul_f32 v[60:61], v[60:61], v[74:75]
	v_pk_mul_f32 v[56:57], v[56:57], v[78:79]
	v_pk_mul_f32 v[52:53], v[52:53], v[136:137]
	v_pk_mul_f32 v[50:51], v[50:51], v[134:135]
	v_pk_mul_f32 v[46:47], v[46:47], v[68:69]
	v_pk_mul_f32 v[42:43], v[42:43], v[72:73]
	v_pk_mul_f32 v[38:39], v[38:39], v[76:77]
	v_pk_mul_f32 v[48:49], v[48:49], v[70:71]
	v_pk_mul_f32 v[44:45], v[44:45], v[74:75]
	v_pk_mul_f32 v[40:41], v[40:41], v[78:79]
	v_pk_mul_f32 v[36:37], v[36:37], v[136:137]
	v_pk_mul_f32 v[34:35], v[34:35], v[134:135]
	v_pk_mul_f32 v[14:15], v[14:15], v[68:69]
	v_pk_mul_f32 v[10:11], v[10:11], v[72:73]
	v_pk_mul_f32 v[6:7], v[6:7], v[76:77]
	v_pk_mul_f32 v[16:17], v[16:17], v[70:71]
	v_pk_mul_f32 v[12:13], v[12:13], v[74:75]
	v_pk_mul_f32 v[8:9], v[8:9], v[78:79]
	v_pk_mul_f32 v[4:5], v[4:5], v[136:137]
	v_pk_mul_f32 v[2:3], v[2:3], v[134:135]

; __device__ __forceinline__ void partialSM(f32x16& p0, f32x16& p1, float& m_reg, float& mn, float& alpha) {
;   constexpr float C = SCALE * 1.4426950408889634f;
;   float pmax = p0[0]; for (int r = 1; r < 16; ++r) pmax = fmaxf(pmax, p0[r]); for (int r = 0; r < 16; ++r) pmax = fmaxf(pmax, p1[r]);
;   { auto rr = __builtin_amdgcn_permlane32_swap(__float_as_uint(pmax), __float_as_uint(pmax), false, false);
;     pmax = fmaxf(__uint_as_float(rr[0]), __uint_as_float(rr[1])); }
;   if (__builtin_expect(__all(pmax - m_reg <= THR / SCALE), 1)) { mn = m_reg; alpha = 1.f; }
;   else { mn = fmaxf(m_reg, pmax); alpha = __builtin_amdgcn_exp2f((m_reg - mn) * C); m_reg = mn; }
;   float mnC = -mn * C;
;   for (int r = 0; r < 16; ++r) p0[r] = fmaf(p0[r], C, mnC); for (int r = 0; r < 16; ++r) p1[r] = fmaf(p1[r], C, mnC);
;   for (int r = 0; r < 16; ++r) p0[r] = __builtin_amdgcn_exp2f(p0[r]);
; }
; __device__ __forceinline__ void pv_mma(f32x16& od, const VFrag& f, bf16x8 pa0, bf16x8 pa1, bf16x8 pa2, bf16x8 pa3) {
;     ...
;   od = __builtin_amdgcn_mfma_f32_32x32x16_bf16(pa0, PK(f.l0, f.h0), od, 0, 0, 0);
;   od = __builtin_amdgcn_mfma_f32_32x32x16_bf16(pa1, PK(f.l1, f.h1), od, 0, 0, 0);
;   od = __builtin_amdgcn_mfma_f32_32x32x16_bf16(pa2, PK(f.l2, f.h2), od, 0, 0, 0);
;   od = __builtin_amdgcn_mfma_f32_32x32x16_bf16(pa3, PK(f.l3, f.h3), od, 0, 0, 0);
;     ...
; }
; __device__ __forceinline__ void pv_d0(f32x16* o, int vb, bf16x8 pa0, bf16x8 pa1, bf16x8 pa2, bf16x8 pa3) {
;   VFrag fa, fb;
;   v_frag_read<0>(fa, vb);
;   asm volatile("s_waitcnt lgkmcnt(0)" ::: "memory"); SBAR();
;   v_frag_read<1>(fb, vb); SBAR();
;   pv_mma(o[0], fa, pa0, pa1, pa2, pa3); SBAR();
;   asm volatile("s_waitcnt lgkmcnt(0)" ::: "memory"); SBAR();
;   v_frag_read<2>(fa, vb); SBAR();
;   pv_mma(o[1], fb, pa0, pa1, pa2, pa3); SBAR();
;   asm volatile("s_waitcnt lgkmcnt(0)" ::: "memory"); SBAR();
;   v_frag_read<3>(fb, vb); SBAR();
;   pv_mma(o[2], fa, pa0, pa1, pa2, pa3); SBAR();
;   asm volatile("s_waitcnt lgkmcnt(0)" ::: "memory"); SBAR();
;   pv_mma(o[3], fb, pa0, pa1, pa2, pa3);
; }
; __device__ __forceinline__ void attn_unit(const bf16* __restrict__ Qb, const bf16* __restrict__ Kh, const bf16* __restrict__ Vh, int klat0, int nlt, int kctx0, int NT,
;                                           float lam, float post, const float* __restrict__ subw, bf16* __restrict__ Ob, char* lds) {
.LBB0_776:
	v_mov_b32_e32 v100, v99
	s_nop 1
	v_permlane32_swap_b32_e32 v99, v100
	v_cvt_pk_bf16_f32 v102, v192, v193
	v_cvt_pk_bf16_f32 v103, v194, v195
	v_cvt_pk_bf16_f32 v104, v196, v197
	v_cvt_pk_bf16_f32 v105, v198, v199
	s_waitcnt lgkmcnt(8)
	v_mfma_f32_32x32x16_bf16 v[66:81], v[174:177], v[114:117], v[66:81]
	v_cvt_pk_bf16_f32 v106, v200, v201
	v_cvt_pk_bf16_f32 v107, v202, v203
	v_cvt_pk_bf16_f32 v108, v204, v205
	v_cvt_pk_bf16_f32 v109, v206, v207
	v_cvt_pk_bf16_f32 v110, v210, v211
	v_cvt_pk_bf16_f32 v111, v212, v213
	v_cvt_pk_bf16_f32 v112, v214, v215
	v_cvt_pk_bf16_f32 v113, v149, v150
	v_cvt_pk_bf16_f32 v134, v151, v186
	v_cvt_pk_bf16_f32 v135, v187, v188
	v_cvt_pk_bf16_f32 v136, v189, v208
	v_cvt_pk_bf16_f32 v137, v209, v148
	v_permlane32_swap_b32_e32 v102, v104
	v_permlane32_swap_b32_e32 v103, v105
	v_permlane32_swap_b32_e32 v106, v108
	v_permlane32_swap_b32_e32 v107, v109
	v_permlane32_swap_b32_e32 v110, v112
	v_permlane32_swap_b32_e32 v111, v113
	v_permlane32_swap_b32_e32 v134, v136
	v_permlane32_swap_b32_e32 v135, v137
	ds_read_b64_tr_b16 v[204:205], v244 offset:0x200
	ds_read_b64_tr_b16 v[206:207], v244 offset:0xa00
	ds_read_b64_tr_b16 v[208:209], v244 offset:0x1200
	ds_read_b64_tr_b16 v[210:211], v244 offset:0x1a00
	ds_read_b64_tr_b16 v[212:213], v244 offset:0x2200
	ds_read_b64_tr_b16 v[214:215], v244 offset:0x2a00
	ds_read_b64_tr_b16 v[216:217], v244 offset:0x3200
	ds_read_b64_tr_b16 v[218:219], v244 offset:0x3a00
	s_waitcnt lgkmcnt(14)
	v_mfma_f32_32x32x16_bf16 v[18:33], v[102:105], v[228:231], v[18:33]
	v_max_f32_e32 v245, v82, v83
	v_max3_f32 v245, v245, v84, v85
	v_max3_f32 v245, v245, v86, v87
	v_max3_f32 v245, v245, v88, v89
	v_max3_f32 v245, v245, v90, v91
	v_max3_f32 v245, v245, v92, v93
	s_waitcnt lgkmcnt(12)
	v_mfma_f32_32x32x16_bf16 v[18:33], v[106:109], v[232:235], v[18:33]
	v_max3_f32 v245, v245, v94, v95
	v_max3_f32 v245, v245, v96, v97
	v_max3_f32 v245, v245, v66, v67
	v_max3_f32 v245, v245, v68, v69
	v_max3_f32 v245, v245, v70, v71
	v_max3_f32 v245, v245, v72, v73
	v_max3_f32 v245, v245, v74, v75
	v_max3_f32 v245, v245, v76, v77
	s_waitcnt lgkmcnt(10)
	v_mfma_f32_32x32x16_bf16 v[18:33], v[110:113], v[236:239], v[18:33]
	v_max3_f32 v245, v245, v78, v79
	v_max3_f32 v245, v245, v80, v81
	v_mov_b32_e32 v246, v245
	s_nop 1
	v_permlane32_swap_b32_e32 v245, v246
	v_max_f32_e32 v245, v245, v246
	v_sub_f32_e32 v246, v245, v133
	s_waitcnt lgkmcnt(8)
	v_mfma_f32_32x32x16_bf16 v[18:33], v[134:137], v[240:243], v[18:33]
	v_cmp_ge_f32_e32 vcc, s63, v246
	v_max_f32_e32 v245, v133, v245
	v_sub_f32_e32 v246, v133, v245
	v_mul_f32_e32 v246, 0x3e38aa3b, v246
	v_exp_f32_e32 v246, v246
	s_cmp_eq_u64 vcc, exec
	s_cselect_b64 s[0:1], -1, 0
	v_cndmask_b32_e64 v247, v246, 1.0, s[0:1]
	ds_read_b64_tr_b16 v[228:229], v244 offset:0x400
	ds_read_b64_tr_b16 v[230:231], v244 offset:0xc00
	ds_read_b64_tr_b16 v[232:233], v244 offset:0x1400
	ds_read_b64_tr_b16 v[234:235], v244 offset:0x1c00
	ds_read_b64_tr_b16 v[236:237], v244 offset:0x2400
	ds_read_b64_tr_b16 v[238:239], v244 offset:0x2c00
	ds_read_b64_tr_b16 v[240:241], v244 offset:0x3400
	ds_read_b64_tr_b16 v[242:243], v244 offset:0x3c00
	v_cndmask_b32_e64 v174, v245, v133, s[0:1]
	v_mul_f32_e32 v98, 0xbe38aa3b, v174
	s_waitcnt lgkmcnt(14)
	v_mfma_f32_32x32x16_bf16 v[50:65], v[102:105], v[204:207], v[50:65]
	v_fmamk_f32 v82, v82, 0x3e38aa3b, v98
	v_fmamk_f32 v83, v83, 0x3e38aa3b, v98
	v_fmamk_f32 v84, v84, 0x3e38aa3b, v98
	v_fmamk_f32 v85, v85, 0x3e38aa3b, v98
	s_waitcnt lgkmcnt(12)
	v_mfma_f32_32x32x16_bf16 v[50:65], v[106:109], v[208:211], v[50:65]
	v_fmamk_f32 v86, v86, 0x3e38aa3b, v98
	v_fmamk_f32 v87, v87, 0x3e38aa3b, v98
	v_fmamk_f32 v88, v88, 0x3e38aa3b, v98
	v_fmamk_f32 v89, v89, 0x3e38aa3b, v98
	s_waitcnt lgkmcnt(10)
	v_mfma_f32_32x32x16_bf16 v[50:65], v[110:113], v[212:215], v[50:65]
	v_fmamk_f32 v90, v90, 0x3e38aa3b, v98
	v_fmamk_f32 v91, v91, 0x3e38aa3b, v98
	v_fmamk_f32 v92, v92, 0x3e38aa3b, v98
	v_fmamk_f32 v93, v93, 0x3e38aa3b, v98
	s_waitcnt lgkmcnt(8)
	v_mfma_f32_32x32x16_bf16 v[50:65], v[134:137], v[216:219], v[50:65]
	v_fmamk_f32 v94, v94, 0x3e38aa3b, v98
	v_fmamk_f32 v95, v95, 0x3e38aa3b, v98
	v_fmamk_f32 v96, v96, 0x3e38aa3b, v98
	v_fmamk_f32 v97, v97, 0x3e38aa3b, v98
	ds_read_b64_tr_b16 v[204:205], v244 offset:0x600
	ds_read_b64_tr_b16 v[206:207], v244 offset:0xe00
	ds_read_b64_tr_b16 v[208:209], v244 offset:0x1600
	ds_read_b64_tr_b16 v[210:211], v244 offset:0x1e00
	ds_read_b64_tr_b16 v[212:213], v244 offset:0x2600
	ds_read_b64_tr_b16 v[214:215], v244 offset:0x2e00
	ds_read_b64_tr_b16 v[216:217], v244 offset:0x3600
	ds_read_b64_tr_b16 v[218:219], v244 offset:0x3e00
	s_waitcnt lgkmcnt(14)
	v_mfma_f32_32x32x16_bf16 v[34:49], v[102:105], v[228:231], v[34:49]
	s_mov_b32 s46, 0x3e38aa3b
	v_pk_fma_f32 v[80:81], v[80:81], s[46:47], v[98:99] op_sel_hi:[1,0,0]
	v_pk_fma_f32 v[78:79], v[78:79], s[46:47], v[98:99] op_sel_hi:[1,0,0]
	s_waitcnt lgkmcnt(12)
	v_mfma_f32_32x32x16_bf16 v[34:49], v[106:109], v[232:235], v[34:49]
	v_pk_fma_f32 v[76:77], v[76:77], s[46:47], v[98:99] op_sel_hi:[1,0,0]
	v_pk_fma_f32 v[74:75], v[74:75], s[46:47], v[98:99] op_sel_hi:[1,0,0]
	v_pk_fma_f32 v[72:73], v[72:73], s[46:47], v[98:99] op_sel_hi:[1,0,0]
	s_waitcnt lgkmcnt(10)
	v_mfma_f32_32x32x16_bf16 v[34:49], v[110:113], v[236:239], v[34:49]
	v_pk_fma_f32 v[70:71], v[70:71], s[46:47], v[98:99] op_sel_hi:[1,0,0]
	v_pk_fma_f32 v[68:69], v[68:69], s[46:47], v[98:99] op_sel_hi:[1,0,0]
	v_pk_fma_f32 v[66:67], v[66:67], s[46:47], v[98:99] op_sel_hi:[1,0,0]
	s_waitcnt lgkmcnt(8)
	v_mfma_f32_32x32x16_bf16 v[34:49], v[134:137], v[240:243], v[34:49]
	v_exp_f32_e32 v175, v82
	v_exp_f32_e32 v177, v83
	v_exp_f32_e32 v192, v84
	s_waitcnt lgkmcnt(6)
	v_mfma_f32_32x32x16_bf16 v[2:17], v[102:105], v[204:207], v[2:17]
	v_mov_b32_e32 v205, v247
	v_exp_f32_e32 v204, v97
	v_exp_f32_e32 v195, v85
	v_exp_f32_e32 v196, v86
	v_exp_f32_e32 v199, v87
	v_exp_f32_e32 v200, v88
	s_waitcnt lgkmcnt(4)
	v_mfma_f32_32x32x16_bf16 v[2:17], v[106:109], v[208:211], v[2:17]
	v_exp_f32_e32 v203, v89
	v_exp_f32_e32 v176, v90
	v_exp_f32_e32 v193, v91
	v_exp_f32_e32 v194, v92
	s_waitcnt lgkmcnt(2)
	v_mfma_f32_32x32x16_bf16 v[2:17], v[110:113], v[212:215], v[2:17]
	v_exp_f32_e32 v197, v93
	v_exp_f32_e32 v198, v94
	v_exp_f32_e32 v201, v95
	v_exp_f32_e32 v202, v96
	s_waitcnt lgkmcnt(0)
	v_mfma_f32_32x32x16_bf16 v[2:17], v[134:137], v[216:219], v[2:17]
	v_add_u32_e32 v245, s100, v169
	v_add_u32_e32 v246, s100, v170
	v_add_u32_e32 v247, s100, v171
	v_add_u32_e32 v255, s100, v172
	v_cmp_gt_f32_e32 vcc, 1.0, v205
	s_cbranch_vccz .LBB0_780
	s_and_saveexec_b64 s[12:13], s[40:41]
	ds_write_b32 v162, v205 offset:128
	s_or_b64 exec, exec, s[12:13]
	s_waitcnt lgkmcnt(0)
	v_add_u32_e32 v101, s18, v140
	ds_read_b128 v[102:105], v101 offset:224
	ds_read_b128 v[106:109], v101 offset:192
	ds_read_b128 v[110:113], v101 offset:160
	ds_read_b128 v[134:137], v101 offset:128
	s_waitcnt lgkmcnt(0)
	v_pk_mul_f32 v[30:31], v[30:31], v[102:103]
	v_pk_mul_f32 v[26:27], v[26:27], v[106:107]
	v_pk_mul_f32 v[22:23], v[22:23], v[110:111]
	v_pk_mul_f32 v[32:33], v[32:33], v[104:105]
	v_pk_mul_f32 v[28:29], v[28:29], v[108:109]
	v_pk_mul_f32 v[24:25], v[24:25], v[112:113]
	v_pk_mul_f32 v[20:21], v[20:21], v[136:137]
	v_pk_mul_f32 v[18:19], v[18:19], v[134:135]
	v_pk_mul_f32 v[62:63], v[62:63], v[102:103]
	v_pk_mul_f32 v[58:59], v[58:59], v[106:107]
	v_pk_mul_f32 v[54:55], v[54:55], v[110:111]
	v_pk_mul_f32 v[64:65], v[64:65], v[104:105]
	v_pk_mul_f32 v[60:61], v[60:61], v[108:109]
	v_pk_mul_f32 v[56:57], v[56:57], v[112:113]
	v_pk_mul_f32 v[52:53], v[52:53], v[136:137]
	v_pk_mul_f32 v[50:51], v[50:51], v[134:135]
	v_pk_mul_f32 v[46:47], v[46:47], v[102:103]
	v_pk_mul_f32 v[42:43], v[42:43], v[106:107]
	v_pk_mul_f32 v[38:39], v[38:39], v[110:111]
	v_pk_mul_f32 v[48:49], v[48:49], v[104:105]
	v_pk_mul_f32 v[44:45], v[44:45], v[108:109]
	v_pk_mul_f32 v[40:41], v[40:41], v[112:113]
	v_pk_mul_f32 v[36:37], v[36:37], v[136:137]
	v_pk_mul_f32 v[34:35], v[34:35], v[134:135]
	v_pk_mul_f32 v[14:15], v[14:15], v[102:103]
	v_pk_mul_f32 v[10:11], v[10:11], v[106:107]
	v_pk_mul_f32 v[6:7], v[6:7], v[110:111]
	v_pk_mul_f32 v[16:17], v[16:17], v[104:105]
	v_pk_mul_f32 v[12:13], v[12:13], v[108:109]
	v_pk_mul_f32 v[8:9], v[8:9], v[112:113]
	v_pk_mul_f32 v[4:5], v[4:5], v[136:137]
	v_pk_mul_f32 v[2:3], v[2:3], v[134:135]
